# conv-gate and final-norm loops: no longer drain the previous item's stores before issuing the next loads
# speedup vs baseline: 1.0186x; 1.0109x over previous
.LBB0_85:
	s_ashr_i32 s1, s0, 31
	s_add_i32 s8, s0, 1
	s_lshl_b64 s[2:3], s[0:1], 11
	s_ashr_i32 s9, s8, 31
	s_add_i32 s4, s0, 2
	v_lshl_add_u64 v[0:1], v[40:41], 0, s[2:3]
	s_lshl_b64 s[2:3], s[8:9], 11
	s_ashr_i32 s5, s4, 31
	global_load_dwordx4 v[46:49], v[0:1], off
	global_load_dwordx4 v[50:53], v[0:1], off offset:1024
	v_lshl_add_u64 v[0:1], v[40:41], 0, s[2:3]
	s_lshl_b64 s[2:3], s[4:5], 11
	global_load_dwordx4 v[36:39], v[0:1], off
	global_load_dwordx4 v[32:35], v[0:1], off offset:1024
	v_lshl_add_u64 v[0:1], v[40:41], 0, s[2:3]
	s_add_i32 s2, s0, 3
	s_ashr_i32 s3, s2, 31
	s_lshl_b64 s[10:11], s[2:3], 11
	global_load_dwordx4 v[28:31], v[0:1], off
	global_load_dwordx4 v[24:27], v[0:1], off offset:1024
	v_lshl_add_u64 v[0:1], v[40:41], 0, s[10:11]
	s_lshl_b64 s[10:11], s[0:1], 2
	s_add_u32 s10, s18, s10
	s_addc_u32 s11, s19, s11
	global_load_dwordx4 v[20:23], v[0:1], off
	global_load_dwordx4 v[4:7], v[0:1], off offset:1024
	global_load_dwordx4 v[12:15], v[42:43], off offset:16
	global_load_dwordx4 v[16:19], v[42:43], off
	s_nop 0
	global_load_dwordx4 v[0:3], v[42:43], off offset:2064
	global_load_dwordx4 v[8:11], v[42:43], off offset:2048
	global_load_dword v54, v153, s[10:11]
	global_load_dword v62, v153, s[10:11] offset:4
	global_load_dword v63, v153, s[10:11] offset:8
	global_load_dword v64, v153, s[10:11] offset:12
	s_lshl_b64 s[10:11], s[0:1], 12
	s_waitcnt vmcnt(0)
	v_lshlrev_b32_e32 v56, 16, v46
	v_and_b32_e32 v57, 0xffff0000, v46
	v_lshlrev_b32_e32 v46, 16, v47
	v_and_b32_e32 v47, 0xffff0000, v47
	v_lshlrev_b32_e32 v58, 16, v48
	v_and_b32_e32 v59, 0xffff0000, v48
	v_lshlrev_b32_e32 v60, 16, v49
	v_and_b32_e32 v61, 0xffff0000, v49
	s_waitcnt vmcnt(0)
	v_fmamk_f32 v54, v54, 0x3a800000, v214
	v_cmp_gt_f32_e32 vcc, s25, v54
	v_mul_f32_e32 v55, 0x4b800000, v54
	s_nop 0
	v_cndmask_b32_e32 v54, v54, v55, vcc
	v_rsq_f32_e32 v54, v54
	s_nop 0
	v_mul_f32_e32 v55, 0x45800000, v54
	v_cndmask_b32_e32 v54, v54, v55, vcc
	v_pk_mul_f32 v[56:57], v[54:55], v[56:57] op_sel_hi:[0,1]
	v_pk_mul_f32 v[46:47], v[54:55], v[46:47] op_sel_hi:[0,1]
	v_pk_mul_f32 v[48:49], v[18:19], v[46:47]
	v_pk_mul_f32 v[46:47], v[16:17], v[56:57]
	v_lshl_add_u64 v[56:57], v[44:45], 0, s[10:11]
	global_store_dwordx4 v[56:57], v[46:49], off
	s_lshl_b64 s[10:11], s[8:9], 2
	s_add_u32 s10, s18, s10
	v_pk_mul_f32 v[46:47], v[54:55], v[58:59] op_sel_hi:[0,1]
	v_pk_mul_f32 v[48:49], v[54:55], v[60:61] op_sel_hi:[0,1]
	v_pk_mul_f32 v[48:49], v[14:15], v[48:49]
	v_pk_mul_f32 v[46:47], v[12:13], v[46:47]
	global_store_dwordx4 v[56:57], v[46:49], off offset:16
	s_addc_u32 s11, s19, s11
	s_lshl_b64 s[8:9], s[8:9], 12
	v_lshlrev_b32_e32 v46, 16, v50
	v_and_b32_e32 v47, 0xffff0000, v50
	v_lshlrev_b32_e32 v48, 16, v51
	v_and_b32_e32 v49, 0xffff0000, v51
	v_pk_mul_f32 v[46:47], v[54:55], v[46:47] op_sel_hi:[0,1]
	v_pk_mul_f32 v[48:49], v[54:55], v[48:49] op_sel_hi:[0,1]
	v_lshlrev_b32_e32 v50, 16, v52
	v_and_b32_e32 v51, 0xffff0000, v52
	v_lshlrev_b32_e32 v52, 16, v53
	v_and_b32_e32 v53, 0xffff0000, v53
	v_pk_mul_f32 v[48:49], v[10:11], v[48:49]
	v_pk_mul_f32 v[46:47], v[8:9], v[46:47]
	global_store_dwordx4 v[56:57], v[46:49], off offset:2048
	s_nop 1
	v_pk_mul_f32 v[46:47], v[54:55], v[50:51] op_sel_hi:[0,1]
	v_pk_mul_f32 v[48:49], v[54:55], v[52:53] op_sel_hi:[0,1]
	v_pk_mul_f32 v[48:49], v[2:3], v[48:49]
	v_pk_mul_f32 v[46:47], v[0:1], v[46:47]
	global_store_dwordx4 v[56:57], v[46:49], off offset:2064
	s_nop 1
	v_mov_b32_e32 v46, v62
	v_lshlrev_b32_e32 v50, 16, v38
	v_lshlrev_b32_e32 v48, 16, v36
	v_and_b32_e32 v49, 0xffff0000, v36
	v_lshlrev_b32_e32 v36, 16, v37
	v_and_b32_e32 v37, 0xffff0000, v37
	v_and_b32_e32 v51, 0xffff0000, v38
	v_lshlrev_b32_e32 v52, 16, v39
	v_and_b32_e32 v53, 0xffff0000, v39
	v_fmamk_f32 v46, v46, 0x3a800000, v214
	v_cmp_gt_f32_e32 vcc, s25, v46
	v_mul_f32_e32 v47, 0x4b800000, v46
	s_nop 0
	v_cndmask_b32_e32 v46, v46, v47, vcc
	v_rsq_f32_e32 v46, v46
	s_nop 0
	v_mul_f32_e32 v47, 0x45800000, v46
	v_cndmask_b32_e32 v46, v46, v47, vcc
	v_pk_mul_f32 v[48:49], v[46:47], v[48:49] op_sel_hi:[0,1]
	v_pk_mul_f32 v[36:37], v[46:47], v[36:37] op_sel_hi:[0,1]
	v_pk_mul_f32 v[38:39], v[18:19], v[36:37]
	v_pk_mul_f32 v[36:37], v[16:17], v[48:49]
	v_lshl_add_u64 v[48:49], v[44:45], 0, s[8:9]
	global_store_dwordx4 v[48:49], v[36:39], off
	s_lshl_b64 s[8:9], s[4:5], 2
	s_add_u32 s8, s18, s8
	v_pk_mul_f32 v[36:37], v[46:47], v[50:51] op_sel_hi:[0,1]
	v_pk_mul_f32 v[38:39], v[46:47], v[52:53] op_sel_hi:[0,1]
	v_pk_mul_f32 v[38:39], v[14:15], v[38:39]
	v_pk_mul_f32 v[36:37], v[12:13], v[36:37]
	global_store_dwordx4 v[48:49], v[36:39], off offset:16
	v_lshlrev_b32_e32 v50, 16, v35
	v_and_b32_e32 v51, 0xffff0000, v35
	v_lshlrev_b32_e32 v36, 16, v32
	v_and_b32_e32 v37, 0xffff0000, v32
	v_lshlrev_b32_e32 v32, 16, v33
	v_and_b32_e32 v33, 0xffff0000, v33
	v_pk_mul_f32 v[36:37], v[46:47], v[36:37] op_sel_hi:[0,1]
	v_pk_mul_f32 v[32:33], v[46:47], v[32:33] op_sel_hi:[0,1]
	v_lshlrev_b32_e32 v38, 16, v34
	v_and_b32_e32 v39, 0xffff0000, v34
	v_pk_mul_f32 v[34:35], v[10:11], v[32:33]
	v_pk_mul_f32 v[32:33], v[8:9], v[36:37]
	global_store_dwordx4 v[48:49], v[32:35], off offset:2048
	s_addc_u32 s9, s19, s9
	s_lshl_b64 s[4:5], s[4:5], 12
	v_pk_mul_f32 v[32:33], v[46:47], v[38:39] op_sel_hi:[0,1]
	v_pk_mul_f32 v[34:35], v[46:47], v[50:51] op_sel_hi:[0,1]
	v_pk_mul_f32 v[34:35], v[2:3], v[34:35]
	v_pk_mul_f32 v[32:33], v[0:1], v[32:33]
	global_store_dwordx4 v[48:49], v[32:35], off offset:2064
	s_nop 1
	v_mov_b32_e32 v32, v63
	v_lshlrev_b32_e32 v36, 16, v30
	v_lshlrev_b32_e32 v34, 16, v28
	v_and_b32_e32 v35, 0xffff0000, v28
	v_lshlrev_b32_e32 v28, 16, v29
	v_and_b32_e32 v29, 0xffff0000, v29
	v_and_b32_e32 v37, 0xffff0000, v30
	v_lshlrev_b32_e32 v38, 16, v31
	v_and_b32_e32 v39, 0xffff0000, v31
	v_fmamk_f32 v32, v32, 0x3a800000, v214
	v_cmp_gt_f32_e32 vcc, s25, v32
	v_mul_f32_e32 v33, 0x4b800000, v32
	s_nop 0
	v_cndmask_b32_e32 v32, v32, v33, vcc
	v_rsq_f32_e32 v32, v32
	s_nop 0
	v_mul_f32_e32 v33, 0x45800000, v32
	v_cndmask_b32_e32 v32, v32, v33, vcc
	v_pk_mul_f32 v[34:35], v[32:33], v[34:35] op_sel_hi:[0,1]
	v_pk_mul_f32 v[28:29], v[32:33], v[28:29] op_sel_hi:[0,1]
	v_pk_mul_f32 v[30:31], v[18:19], v[28:29]
	v_pk_mul_f32 v[28:29], v[16:17], v[34:35]
	v_lshl_add_u64 v[34:35], v[44:45], 0, s[4:5]
	global_store_dwordx4 v[34:35], v[28:31], off
	s_lshl_b64 s[4:5], s[2:3], 2
	s_add_u32 s4, s18, s4
	v_pk_mul_f32 v[28:29], v[32:33], v[36:37] op_sel_hi:[0,1]
	v_pk_mul_f32 v[30:31], v[32:33], v[38:39] op_sel_hi:[0,1]
	v_pk_mul_f32 v[30:31], v[14:15], v[30:31]
	v_pk_mul_f32 v[28:29], v[12:13], v[28:29]
	global_store_dwordx4 v[34:35], v[28:31], off offset:16
	v_lshlrev_b32_e32 v36, 16, v27
	v_and_b32_e32 v37, 0xffff0000, v27
	v_lshlrev_b32_e32 v28, 16, v24
	v_and_b32_e32 v29, 0xffff0000, v24
	v_lshlrev_b32_e32 v24, 16, v25
	v_and_b32_e32 v25, 0xffff0000, v25
	v_pk_mul_f32 v[28:29], v[32:33], v[28:29] op_sel_hi:[0,1]
	v_pk_mul_f32 v[24:25], v[32:33], v[24:25] op_sel_hi:[0,1]
	v_lshlrev_b32_e32 v30, 16, v26
	v_and_b32_e32 v31, 0xffff0000, v26
	v_pk_mul_f32 v[26:27], v[10:11], v[24:25]
	v_pk_mul_f32 v[24:25], v[8:9], v[28:29]
	global_store_dwordx4 v[34:35], v[24:27], off offset:2048
	s_addc_u32 s5, s19, s5
	s_lshl_b64 s[2:3], s[2:3], 12
	v_pk_mul_f32 v[24:25], v[32:33], v[30:31] op_sel_hi:[0,1]
	v_pk_mul_f32 v[26:27], v[32:33], v[36:37] op_sel_hi:[0,1]
	v_pk_mul_f32 v[26:27], v[2:3], v[26:27]
	v_pk_mul_f32 v[24:25], v[0:1], v[24:25]
	global_store_dwordx4 v[34:35], v[24:27], off offset:2064
	s_nop 1
	v_mov_b32_e32 v24, v64
	v_lshlrev_b32_e32 v28, 16, v22
	v_lshlrev_b32_e32 v26, 16, v20
	v_and_b32_e32 v27, 0xffff0000, v20
	v_lshlrev_b32_e32 v20, 16, v21
	v_and_b32_e32 v21, 0xffff0000, v21
	v_and_b32_e32 v29, 0xffff0000, v22
	v_lshlrev_b32_e32 v22, 16, v23
	v_and_b32_e32 v23, 0xffff0000, v23
	s_add_i32 s13, s13, s29
	s_add_i32 s0, s0, s24
	s_cmpk_gt_i32 s13, 0x1fff
	v_fmamk_f32 v24, v24, 0x3a800000, v214
	v_cmp_gt_f32_e32 vcc, s25, v24
	v_mul_f32_e32 v25, 0x4b800000, v24
	s_nop 0
	v_cndmask_b32_e32 v24, v24, v25, vcc
	v_rsq_f32_e32 v24, v24
	s_nop 0
	v_mul_f32_e32 v25, 0x45800000, v24
	v_cndmask_b32_e32 v24, v24, v25, vcc
	v_pk_mul_f32 v[26:27], v[24:25], v[26:27] op_sel_hi:[0,1]
	v_pk_mul_f32 v[20:21], v[24:25], v[20:21] op_sel_hi:[0,1]
	v_pk_mul_f32 v[18:19], v[18:19], v[20:21]
	v_pk_mul_f32 v[16:17], v[16:17], v[26:27]
	v_lshl_add_u64 v[20:21], v[44:45], 0, s[2:3]
	global_store_dwordx4 v[20:21], v[16:19], off
	s_nop 1
	v_pk_mul_f32 v[16:17], v[24:25], v[28:29] op_sel_hi:[0,1]
	v_pk_mul_f32 v[18:19], v[24:25], v[22:23] op_sel_hi:[0,1]
	v_pk_mul_f32 v[14:15], v[14:15], v[18:19]
	v_pk_mul_f32 v[12:13], v[12:13], v[16:17]
	global_store_dwordx4 v[20:21], v[12:15], off offset:16
	v_lshlrev_b32_e32 v16, 16, v7
	v_and_b32_e32 v17, 0xffff0000, v7
	v_lshlrev_b32_e32 v12, 16, v4
	v_and_b32_e32 v13, 0xffff0000, v4
	v_lshlrev_b32_e32 v4, 16, v5
	v_and_b32_e32 v5, 0xffff0000, v5
	v_pk_mul_f32 v[12:13], v[24:25], v[12:13] op_sel_hi:[0,1]
	v_pk_mul_f32 v[4:5], v[24:25], v[4:5] op_sel_hi:[0,1]
	v_lshlrev_b32_e32 v14, 16, v6
	v_and_b32_e32 v15, 0xffff0000, v6
	v_pk_mul_f32 v[6:7], v[10:11], v[4:5]
	v_pk_mul_f32 v[4:5], v[8:9], v[12:13]
	global_store_dwordx4 v[20:21], v[4:7], off offset:2048
	s_nop 1
	v_pk_mul_f32 v[4:5], v[24:25], v[14:15] op_sel_hi:[0,1]
	v_pk_mul_f32 v[6:7], v[24:25], v[16:17] op_sel_hi:[0,1]
	v_pk_mul_f32 v[2:3], v[2:3], v[6:7]
	v_pk_mul_f32 v[0:1], v[0:1], v[4:5]
	global_store_dwordx4 v[20:21], v[0:3], off offset:2064
	s_cbranch_scc0 .LBB0_85

.LBB0_185:
	s_and_b32 s4, s2, 0x300
	v_or_b32_e32 v12, s4, v54
	v_readlane_b32 s4, v252, 31
	v_lshlrev_b32_e32 v4, 2, v12
	v_readlane_b32 s5, v252, 32
	global_load_dwordx4 v[0:3], v4, s[58:59]
	v_readlane_b32 s18, v251, 6
	v_readlane_b32 s19, v251, 7
	v_lshlrev_b32_e32 v152, 1, v12
	s_nop 0
	global_load_dwordx4 v[8:11], v4, s[4:5]
	v_readlane_b32 s4, v252, 49
	v_readlane_b32 s5, v252, 50
	s_nop 4
	global_load_dwordx4 v[4:7], v4, s[4:5]
	s_and_b32 s4, s3, -8
	s_cmp_lt_i32 s4, 0x8000
	s_movk_i32 s5, 0x7f8
	s_cselect_b32 s9, s5, 0xf8
	s_ashr_i32 s5, s4, 31
	s_and_b32 s11, s9, s3
	s_lshl_b64 s[12:13], s[4:5], 11
	s_add_u32 s12, s18, s12
	s_addc_u32 s13, s19, s13
	s_cmp_eq_u32 s11, 0
	v_lshl_add_u64 v[16:17], s[12:13], 0, v[152:153]
	s_cbranch_scc1 .LBB0_187
	global_load_dwordx2 v[24:25], v[16:17], off offset:-2048
	s_branch .LBB0_188
